# v106 plus s_setprio 1 for the wr==0 wave half across the P8 SwiGLU epilogue (post-barrier VALU segment), reset to 0 at the epilogue end
# baseline (speedup 1.0000x reference)
.LBB0_547:
	ds_read_b128 v[154:157], v149
	ds_read_b128 v[158:161], v149 offset:1024
	ds_read_b128 v[162:165], v149 offset:2048
	ds_read_b128 v[166:169], v149 offset:3072
	ds_read_b128 v[170:173], v150
	ds_read_b128 v[174:177], v150 offset:1024
	ds_read_b128 v[182:185], v150 offset:2048
	ds_read_b128 v[186:189], v150 offset:3072
	s_add_u32 s12, s10, 0xfffc0080
	s_addc_u32 s13, s11, -1
	s_cmp_eq_u32 s25, 12
	s_cselect_b32 s45, s37, s13
	s_cselect_b32 s44, s36, s12
	s_cselect_b32 s13, s43, s9
	s_cselect_b32 s12, s42, s1
	v_lshl_add_u64 v[144:145], s[10:11], 0, v[136:137]
	s_add_i32 m0, s48, 0xc000
	ds_read_b128 v[190:193], v151
	ds_read_b128 v[194:197], v151 offset:1024
	ds_read_b128 v[198:201], v151 offset:2048
	ds_read_b128 v[202:205], v151 offset:3072
	ds_read_b128 v[206:209], v151 offset:4096
	ds_read_b128 v[210:213], v151 offset:5120
	ds_read_b128 v[214:217], v151 offset:6144
	ds_read_b128 v[218:221], v151 offset:7168
	global_load_lds_dwordx4 v[144:145], off
	v_lshl_add_u64 v[144:145], s[10:11], 0, v[138:139]
	s_add_i32 m0, s48, 0xe000
	s_nop 0
	global_load_lds_dwordx4 v[144:145], off
	s_waitcnt vmcnt(8)
	s_waitcnt lgkmcnt(0)
	s_barrier
	s_setprio 1
	s_waitcnt lgkmcnt(0)
	v_mfma_f32_16x16x32_bf16 v[120:123], v[154:157], v[190:193], v[120:123]
	v_mfma_f32_16x16x32_bf16 v[124:127], v[162:165], v[190:193], v[124:127]
	v_mfma_f32_16x16x32_bf16 v[108:111], v[154:157], v[198:201], v[108:111]
	v_mfma_f32_16x16x32_bf16 v[104:107], v[162:165], v[198:201], v[104:107]
	v_mfma_f32_16x16x32_bf16 v[92:95], v[154:157], v[206:209], v[92:95]
	v_mfma_f32_16x16x32_bf16 v[88:91], v[162:165], v[206:209], v[88:91]
	v_mfma_f32_16x16x32_bf16 v[76:79], v[154:157], v[214:217], v[76:79]
	v_mfma_f32_16x16x32_bf16 v[72:75], v[162:165], v[214:217], v[72:75]
	v_mfma_f32_16x16x32_bf16 v[120:123], v[158:161], v[194:197], v[120:123]
	v_mfma_f32_16x16x32_bf16 v[124:127], v[166:169], v[194:197], v[124:127]
	v_mfma_f32_16x16x32_bf16 v[108:111], v[158:161], v[202:205], v[108:111]
	v_mfma_f32_16x16x32_bf16 v[104:107], v[166:169], v[202:205], v[104:107]
	v_mfma_f32_16x16x32_bf16 v[92:95], v[158:161], v[210:213], v[92:95]
	v_mfma_f32_16x16x32_bf16 v[88:91], v[166:169], v[210:213], v[88:91]
	v_mfma_f32_16x16x32_bf16 v[76:79], v[158:161], v[218:221], v[76:79]
	v_mfma_f32_16x16x32_bf16 v[72:75], v[166:169], v[218:221], v[72:75]
	s_setprio 0
	s_setprio 1
	v_mfma_f32_16x16x32_bf16 v[116:119], v[170:173], v[190:193], v[116:119]
	v_mfma_f32_16x16x32_bf16 v[112:115], v[182:185], v[190:193], v[112:115]
	v_mfma_f32_16x16x32_bf16 v[100:103], v[170:173], v[198:201], v[100:103]
	v_mfma_f32_16x16x32_bf16 v[96:99], v[182:185], v[198:201], v[96:99]
	v_mfma_f32_16x16x32_bf16 v[84:87], v[170:173], v[206:209], v[84:87]
	v_mfma_f32_16x16x32_bf16 v[80:83], v[182:185], v[206:209], v[80:83]
	v_mfma_f32_16x16x32_bf16 v[68:71], v[170:173], v[214:217], v[68:71]
	v_mfma_f32_16x16x32_bf16 v[64:67], v[182:185], v[214:217], v[64:67]
	v_mfma_f32_16x16x32_bf16 v[116:119], v[174:177], v[194:197], v[116:119]
	v_mfma_f32_16x16x32_bf16 v[112:115], v[186:189], v[194:197], v[112:115]
	v_mfma_f32_16x16x32_bf16 v[100:103], v[174:177], v[202:205], v[100:103]
	v_mfma_f32_16x16x32_bf16 v[96:99], v[186:189], v[202:205], v[96:99]
	v_mfma_f32_16x16x32_bf16 v[84:87], v[174:177], v[210:213], v[84:87]
	v_mfma_f32_16x16x32_bf16 v[80:83], v[186:189], v[210:213], v[80:83]
	v_mfma_f32_16x16x32_bf16 v[68:71], v[174:177], v[218:221], v[68:71]
	v_mfma_f32_16x16x32_bf16 v[64:67], v[186:189], v[218:221], v[64:67]
	s_setprio 0
	s_barrier
	s_add_i32 s26, s56, s46
	v_lshl_add_u64 v[144:145], s[12:13], 0, v[132:133]
	s_mov_b32 m0, s26
	ds_read_b128 v[190:193], v151 offset:16384
	ds_read_b128 v[194:197], v151 offset:17408
	ds_read_b128 v[198:201], v151 offset:18432
	ds_read_b128 v[202:205], v151 offset:19456
	ds_read_b128 v[206:209], v151 offset:20480
	ds_read_b128 v[210:213], v151 offset:21504
	ds_read_b128 v[214:217], v151 offset:22528
	ds_read_b128 v[218:221], v151 offset:23552
	global_load_lds_dwordx4 v[144:145], off
	s_add_i32 m0, s26, 0x2000
	s_add_u32 s26, s12, 0x40000
	v_lshl_add_u64 v[178:179], s[12:13], 0, v[128:129]
	s_addc_u32 s27, s13, 0
	s_add_i32 s29, s57, s46
	global_load_lds_dwordx4 v[178:179], off
	v_lshl_add_u64 v[180:181], s[26:27], 0, v[132:133]
	s_mov_b32 m0, s29
	v_lshl_add_u64 v[222:223], s[44:45], 0, v[130:131]
	global_load_lds_dwordx4 v[180:181], off
	v_lshl_add_u64 v[180:181], s[26:27], 0, v[128:129]
	s_add_i32 m0, s29, 0x2000
	s_nop 0
	global_load_lds_dwordx4 v[180:181], off
	v_lshl_add_u64 v[180:181], s[44:45], 0, v[134:135]
	s_mov_b32 m0, s48
	s_nop 0
	global_load_lds_dwordx4 v[180:181], off
	s_mov_b32 m0, s49
	s_nop 0
	global_load_lds_dwordx4 v[222:223], off
	s_waitcnt vmcnt(8)
	s_waitcnt lgkmcnt(0)
	s_barrier
	s_setprio 1
	s_waitcnt lgkmcnt(0)
	v_mfma_f32_16x16x32_bf16 v[60:63], v[154:157], v[190:193], v[60:63]
	v_mfma_f32_16x16x32_bf16 v[56:59], v[162:165], v[190:193], v[56:59]
	v_mfma_f32_16x16x32_bf16 v[44:47], v[154:157], v[198:201], v[44:47]
	v_mfma_f32_16x16x32_bf16 v[40:43], v[162:165], v[198:201], v[40:43]
	v_mfma_f32_16x16x32_bf16 v[28:31], v[154:157], v[206:209], v[28:31]
	v_mfma_f32_16x16x32_bf16 v[24:27], v[162:165], v[206:209], v[24:27]
	v_mfma_f32_16x16x32_bf16 v[12:15], v[154:157], v[214:217], v[12:15]
	v_mfma_f32_16x16x32_bf16 v[8:11], v[162:165], v[214:217], v[8:11]
	v_mfma_f32_16x16x32_bf16 v[60:63], v[158:161], v[194:197], v[60:63]
	v_mfma_f32_16x16x32_bf16 v[56:59], v[166:169], v[194:197], v[56:59]
	v_mfma_f32_16x16x32_bf16 v[44:47], v[158:161], v[202:205], v[44:47]
	v_mfma_f32_16x16x32_bf16 v[40:43], v[166:169], v[202:205], v[40:43]
	v_mfma_f32_16x16x32_bf16 v[28:31], v[158:161], v[210:213], v[28:31]
	v_mfma_f32_16x16x32_bf16 v[24:27], v[166:169], v[210:213], v[24:27]
	v_mfma_f32_16x16x32_bf16 v[12:15], v[158:161], v[218:221], v[12:15]
	v_mfma_f32_16x16x32_bf16 v[8:11], v[166:169], v[218:221], v[8:11]
	s_setprio 0
	s_setprio 1
	v_mfma_f32_16x16x32_bf16 v[52:55], v[170:173], v[190:193], v[52:55]
	v_mfma_f32_16x16x32_bf16 v[48:51], v[182:185], v[190:193], v[48:51]
	v_mfma_f32_16x16x32_bf16 v[36:39], v[170:173], v[198:201], v[36:39]
	v_mfma_f32_16x16x32_bf16 v[32:35], v[182:185], v[198:201], v[32:35]
	v_mfma_f32_16x16x32_bf16 v[20:23], v[170:173], v[206:209], v[20:23]
	v_mfma_f32_16x16x32_bf16 v[16:19], v[182:185], v[206:209], v[16:19]
	v_mfma_f32_16x16x32_bf16 v[4:7], v[170:173], v[214:217], v[4:7]
	v_mfma_f32_16x16x32_bf16 v[0:3], v[182:185], v[214:217], v[0:3]
	v_mfma_f32_16x16x32_bf16 v[52:55], v[174:177], v[194:197], v[52:55]
	v_mfma_f32_16x16x32_bf16 v[48:51], v[186:189], v[194:197], v[48:51]
	v_mfma_f32_16x16x32_bf16 v[36:39], v[174:177], v[202:205], v[36:39]
	v_mfma_f32_16x16x32_bf16 v[32:35], v[186:189], v[202:205], v[32:35]
	v_mfma_f32_16x16x32_bf16 v[20:23], v[174:177], v[210:213], v[20:23]
	v_mfma_f32_16x16x32_bf16 v[16:19], v[186:189], v[210:213], v[16:19]
	v_mfma_f32_16x16x32_bf16 v[4:7], v[174:177], v[218:221], v[4:7]
	v_mfma_f32_16x16x32_bf16 v[0:3], v[186:189], v[218:221], v[0:3]
	s_setprio 0
	s_barrier
	s_add_i32 s29, 0, 0x18000
	v_add_u32_e32 v153, s29, v147
	s_add_i32 s60, 0, 0x1c000
	ds_read_b128 v[154:157], v153
	ds_read_b128 v[158:161], v153 offset:1024
	ds_read_b128 v[162:165], v153 offset:2048
	ds_read_b128 v[166:169], v153 offset:3072
	v_add_u32_e32 v153, s60, v147
	ds_read_b128 v[170:173], v153
	ds_read_b128 v[174:177], v153 offset:1024
	ds_read_b128 v[182:185], v153 offset:2048
	ds_read_b128 v[186:189], v153 offset:3072
	s_add_u32 s26, s44, 0x40000
	s_addc_u32 s27, s45, 0
	s_mov_b32 m0, s50
	v_lshl_add_u64 v[224:225], s[26:27], 0, v[134:135]
	ds_read_b128 v[190:193], v151 offset:32768
	ds_read_b128 v[194:197], v151 offset:33792
	ds_read_b128 v[198:201], v151 offset:34816
	ds_read_b128 v[202:205], v151 offset:35840
	ds_read_b128 v[206:209], v151 offset:36864
	ds_read_b128 v[210:213], v151 offset:37888
	ds_read_b128 v[214:217], v151 offset:38912
	ds_read_b128 v[218:221], v151 offset:39936
	global_load_lds_dwordx4 v[224:225], off
	v_lshl_add_u64 v[224:225], s[26:27], 0, v[130:131]
	s_mov_b32 m0, s51
	s_nop 0
	global_load_lds_dwordx4 v[224:225], off
	s_waitcnt vmcnt(8)
	s_waitcnt lgkmcnt(0)
	s_barrier
	s_setprio 1
	s_waitcnt lgkmcnt(0)
	v_mfma_f32_16x16x32_bf16 v[120:123], v[154:157], v[190:193], v[120:123]
	v_mfma_f32_16x16x32_bf16 v[124:127], v[162:165], v[190:193], v[124:127]
	v_mfma_f32_16x16x32_bf16 v[108:111], v[154:157], v[198:201], v[108:111]
	v_mfma_f32_16x16x32_bf16 v[104:107], v[162:165], v[198:201], v[104:107]
	v_mfma_f32_16x16x32_bf16 v[92:95], v[154:157], v[206:209], v[92:95]
	v_mfma_f32_16x16x32_bf16 v[88:91], v[162:165], v[206:209], v[88:91]
	v_mfma_f32_16x16x32_bf16 v[76:79], v[154:157], v[214:217], v[76:79]
	v_mfma_f32_16x16x32_bf16 v[72:75], v[162:165], v[214:217], v[72:75]
	v_mfma_f32_16x16x32_bf16 v[120:123], v[158:161], v[194:197], v[120:123]
	v_mfma_f32_16x16x32_bf16 v[124:127], v[166:169], v[194:197], v[124:127]
	v_mfma_f32_16x16x32_bf16 v[108:111], v[158:161], v[202:205], v[108:111]
	v_mfma_f32_16x16x32_bf16 v[104:107], v[166:169], v[202:205], v[104:107]
	v_mfma_f32_16x16x32_bf16 v[92:95], v[158:161], v[210:213], v[92:95]
	v_mfma_f32_16x16x32_bf16 v[88:91], v[166:169], v[210:213], v[88:91]
	v_mfma_f32_16x16x32_bf16 v[76:79], v[158:161], v[218:221], v[76:79]
	v_mfma_f32_16x16x32_bf16 v[72:75], v[166:169], v[218:221], v[72:75]
	s_setprio 0
	s_setprio 1
	v_mfma_f32_16x16x32_bf16 v[116:119], v[170:173], v[190:193], v[116:119]
	v_mfma_f32_16x16x32_bf16 v[112:115], v[182:185], v[190:193], v[112:115]
	v_mfma_f32_16x16x32_bf16 v[100:103], v[170:173], v[198:201], v[100:103]
	v_mfma_f32_16x16x32_bf16 v[96:99], v[182:185], v[198:201], v[96:99]
	v_mfma_f32_16x16x32_bf16 v[84:87], v[170:173], v[206:209], v[84:87]
	v_mfma_f32_16x16x32_bf16 v[80:83], v[182:185], v[206:209], v[80:83]
	v_mfma_f32_16x16x32_bf16 v[68:71], v[170:173], v[214:217], v[68:71]
	v_mfma_f32_16x16x32_bf16 v[64:67], v[182:185], v[214:217], v[64:67]
	v_mfma_f32_16x16x32_bf16 v[116:119], v[174:177], v[194:197], v[116:119]
	v_mfma_f32_16x16x32_bf16 v[112:115], v[186:189], v[194:197], v[112:115]
	v_mfma_f32_16x16x32_bf16 v[100:103], v[174:177], v[202:205], v[100:103]
	v_mfma_f32_16x16x32_bf16 v[96:99], v[186:189], v[202:205], v[96:99]
	v_mfma_f32_16x16x32_bf16 v[84:87], v[174:177], v[210:213], v[84:87]
	v_mfma_f32_16x16x32_bf16 v[80:83], v[186:189], v[210:213], v[80:83]
	v_mfma_f32_16x16x32_bf16 v[68:71], v[174:177], v[218:221], v[68:71]
	v_mfma_f32_16x16x32_bf16 v[64:67], v[186:189], v[218:221], v[64:67]
	s_setprio 0
	s_barrier
	s_add_i32 s26, s29, s46
	v_lshl_add_u64 v[144:145], v[144:145], 0, s[16:17]
	s_mov_b32 m0, s26
	ds_read_b128 v[190:193], v151 offset:49152
	ds_read_b128 v[194:197], v151 offset:50176
	ds_read_b128 v[198:201], v151 offset:51200
	ds_read_b128 v[202:205], v151 offset:52224
	ds_read_b128 v[206:209], v151 offset:53248
	ds_read_b128 v[210:213], v151 offset:54272
	ds_read_b128 v[214:217], v151 offset:55296
	ds_read_b128 v[218:221], v151 offset:56320
	global_load_lds_dwordx4 v[144:145], off
	s_add_i32 m0, s26, 0x2000
	s_add_u32 s12, s12, 0x40080
	v_lshl_add_u64 v[144:145], v[178:179], 0, s[16:17]
	s_addc_u32 s13, s13, 0
	s_add_i32 s26, s60, s46
	global_load_lds_dwordx4 v[144:145], off
	v_lshl_add_u64 v[144:145], s[12:13], 0, v[132:133]
	s_mov_b32 m0, s26
	s_nop 0
	global_load_lds_dwordx4 v[144:145], off
	v_lshl_add_u64 v[144:145], s[12:13], 0, v[128:129]
	s_add_i32 m0, s26, 0x2000
	s_nop 0
	global_load_lds_dwordx4 v[144:145], off
	v_lshl_add_u64 v[144:145], v[180:181], 0, s[16:17]
	s_mov_b32 m0, s53
	s_nop 0
	global_load_lds_dwordx4 v[144:145], off
	v_lshl_add_u64 v[144:145], v[222:223], 0, s[16:17]
	s_mov_b32 m0, s54
	s_nop 0
	global_load_lds_dwordx4 v[144:145], off
	s_waitcnt vmcnt(8)
	s_waitcnt lgkmcnt(0)
	s_barrier
	s_setprio 1
	s_waitcnt lgkmcnt(0)
	v_mfma_f32_16x16x32_bf16 v[60:63], v[154:157], v[190:193], v[60:63]
	v_mfma_f32_16x16x32_bf16 v[56:59], v[162:165], v[190:193], v[56:59]
	v_mfma_f32_16x16x32_bf16 v[44:47], v[154:157], v[198:201], v[44:47]
	v_mfma_f32_16x16x32_bf16 v[40:43], v[162:165], v[198:201], v[40:43]
	v_mfma_f32_16x16x32_bf16 v[28:31], v[154:157], v[206:209], v[28:31]
	v_mfma_f32_16x16x32_bf16 v[24:27], v[162:165], v[206:209], v[24:27]
	v_mfma_f32_16x16x32_bf16 v[12:15], v[154:157], v[214:217], v[12:15]
	v_mfma_f32_16x16x32_bf16 v[8:11], v[162:165], v[214:217], v[8:11]
	v_mfma_f32_16x16x32_bf16 v[60:63], v[158:161], v[194:197], v[60:63]
	v_mfma_f32_16x16x32_bf16 v[56:59], v[166:169], v[194:197], v[56:59]
	v_mfma_f32_16x16x32_bf16 v[44:47], v[158:161], v[202:205], v[44:47]
	v_mfma_f32_16x16x32_bf16 v[40:43], v[166:169], v[202:205], v[40:43]
	v_mfma_f32_16x16x32_bf16 v[28:31], v[158:161], v[210:213], v[28:31]
	v_mfma_f32_16x16x32_bf16 v[24:27], v[166:169], v[210:213], v[24:27]
	v_mfma_f32_16x16x32_bf16 v[12:15], v[158:161], v[218:221], v[12:15]
	v_mfma_f32_16x16x32_bf16 v[8:11], v[166:169], v[218:221], v[8:11]
	s_setprio 0
	s_setprio 1
	v_mfma_f32_16x16x32_bf16 v[52:55], v[170:173], v[190:193], v[52:55]
	v_mfma_f32_16x16x32_bf16 v[48:51], v[182:185], v[190:193], v[48:51]
	v_mfma_f32_16x16x32_bf16 v[36:39], v[170:173], v[198:201], v[36:39]
	v_mfma_f32_16x16x32_bf16 v[32:35], v[182:185], v[198:201], v[32:35]
	v_mfma_f32_16x16x32_bf16 v[20:23], v[170:173], v[206:209], v[20:23]
	v_mfma_f32_16x16x32_bf16 v[16:19], v[182:185], v[206:209], v[16:19]
	v_mfma_f32_16x16x32_bf16 v[4:7], v[170:173], v[214:217], v[4:7]
	v_mfma_f32_16x16x32_bf16 v[0:3], v[182:185], v[214:217], v[0:3]
	v_mfma_f32_16x16x32_bf16 v[52:55], v[174:177], v[194:197], v[52:55]
	v_mfma_f32_16x16x32_bf16 v[48:51], v[186:189], v[194:197], v[48:51]
	v_mfma_f32_16x16x32_bf16 v[36:39], v[174:177], v[202:205], v[36:39]
	v_mfma_f32_16x16x32_bf16 v[32:35], v[186:189], v[202:205], v[32:35]
	v_mfma_f32_16x16x32_bf16 v[20:23], v[174:177], v[210:213], v[20:23]
	v_mfma_f32_16x16x32_bf16 v[16:19], v[186:189], v[210:213], v[16:19]
	v_mfma_f32_16x16x32_bf16 v[4:7], v[174:177], v[218:221], v[4:7]
	v_mfma_f32_16x16x32_bf16 v[0:3], v[186:189], v[218:221], v[0:3]
	s_setprio 0
	s_barrier
	s_add_i32 s25, s25, 2
	s_add_u32 s10, s10, 0x100
	s_addc_u32 s11, s11, 0
	s_add_u32 s1, s1, 0x100
	s_addc_u32 s9, s9, 0
	s_cmp_gt_u32 s25, 13
	s_cbranch_scc0 .LBB0_547
	s_and_b64 vcc, exec, s[18:19]
	s_cbranch_vccz .LBB0_550
	s_barrier
	s_setprio 1

.Lp8_nonext:
	v_lshl_add_u32 v214, s8, 8, v146
	v_lshl_or_b32 v215, s0, 7, v148
	v_mul_u32_u24_e32 v154, 0x1600, v214
	v_lshl_add_u32 v154, v215, 1, v154
	v_add_u32_e32 v155, 0x16000, v154
	v_add_u32_e32 v156, 0x2c000, v154
	v_add_u32_e32 v157, 0x42000, v154
	v_add_u32_e32 v158, 0xb0000, v154
	v_add_u32_e32 v159, 0xc6000, v154
	v_add_u32_e32 v160, 0xdc000, v154
	v_add_u32_e32 v161, 0xf2000, v154
	s_waitcnt lgkmcnt(0)
	v_add_f32_e32 v174, v174, v175
	v_add_f32_e32 v178, v178, v179
	v_add_f32_e32 v182, v182, v183
	v_add_f32_e32 v186, v186, v187
	v_add_f32_e32 v190, v190, v191
	v_add_f32_e32 v194, v194, v195
	v_add_f32_e32 v198, v198, v199
	v_add_f32_e32 v202, v202, v203
	v_add_f32_e32 v174, v174, v176
	v_add_f32_e32 v178, v178, v180
	v_add_f32_e32 v182, v182, v184
	v_add_f32_e32 v186, v186, v188
	v_add_f32_e32 v190, v190, v192
	v_add_f32_e32 v194, v194, v196
	v_add_f32_e32 v198, v198, v200
	v_add_f32_e32 v202, v202, v204
	v_add_f32_e32 v174, v174, v177
	v_add_f32_e32 v178, v178, v181
	v_add_f32_e32 v182, v182, v185
	v_add_f32_e32 v186, v186, v189
	v_add_f32_e32 v190, v190, v193
	v_add_f32_e32 v194, v194, v197
	v_add_f32_e32 v198, v198, v201
	v_add_f32_e32 v202, v202, v205
	v_fmamk_f32 v174, v174, 0x3a800000, v152
	v_fmamk_f32 v178, v178, 0x3a800000, v152
	v_fmamk_f32 v182, v182, 0x3a800000, v152
	v_fmamk_f32 v186, v186, 0x3a800000, v152
	v_fmamk_f32 v190, v190, 0x3a800000, v152
	v_fmamk_f32 v194, v194, 0x3a800000, v152
	v_fmamk_f32 v198, v198, 0x3a800000, v152
	v_fmamk_f32 v202, v202, 0x3a800000, v152
	v_mul_f32_e32 v175, 0x4b800000, v174
	v_mul_f32_e32 v179, 0x4b800000, v178
	v_mul_f32_e32 v183, 0x4b800000, v182
	v_mul_f32_e32 v187, 0x4b800000, v186
	v_mul_f32_e32 v191, 0x4b800000, v190
	v_mul_f32_e32 v195, 0x4b800000, v194
	v_mul_f32_e32 v199, 0x4b800000, v198
	v_mul_f32_e32 v203, 0x4b800000, v202
	v_cmp_gt_f32_e64 s[74:75], s58, v174
	v_cmp_gt_f32_e64 s[76:77], s58, v178
	v_cmp_gt_f32_e64 s[78:79], s58, v182
	v_cmp_gt_f32_e64 s[80:81], s58, v186
	v_cmp_gt_f32_e64 s[82:83], s58, v190
	v_cmp_gt_f32_e64 s[84:85], s58, v194
	v_cmp_gt_f32_e64 s[86:87], s58, v198
	v_cmp_gt_f32_e64 s[88:89], s58, v202
	v_cndmask_b32_e64 v174, v174, v175, s[74:75]
	v_cndmask_b32_e64 v178, v178, v179, s[76:77]
	v_cndmask_b32_e64 v182, v182, v183, s[78:79]
	v_cndmask_b32_e64 v186, v186, v187, s[80:81]
	v_cndmask_b32_e64 v190, v190, v191, s[82:83]
	v_cndmask_b32_e64 v194, v194, v195, s[84:85]
	v_cndmask_b32_e64 v198, v198, v199, s[86:87]
	v_cndmask_b32_e64 v202, v202, v203, s[88:89]
	v_rsq_f32_e32 v174, v174
	v_rsq_f32_e32 v178, v178
	v_rsq_f32_e32 v182, v182
	v_rsq_f32_e32 v186, v186
	v_rsq_f32_e32 v190, v190
	v_rsq_f32_e32 v194, v194
	v_rsq_f32_e32 v198, v198
	v_rsq_f32_e32 v202, v202
	v_mul_f32_e32 v175, 0x45800000, v174
	v_mul_f32_e32 v179, 0x45800000, v178
	v_mul_f32_e32 v183, 0x45800000, v182
	v_mul_f32_e32 v187, 0x45800000, v186
	v_mul_f32_e32 v191, 0x45800000, v190
	v_mul_f32_e32 v195, 0x45800000, v194
	v_mul_f32_e32 v199, 0x45800000, v198
	v_mul_f32_e32 v203, 0x45800000, v202
	v_cndmask_b32_e64 v206, v174, v175, s[74:75]
	v_cndmask_b32_e64 v207, v178, v179, s[76:77]
	v_cndmask_b32_e64 v208, v182, v183, s[78:79]
	v_cndmask_b32_e64 v209, v186, v187, s[80:81]
	v_cndmask_b32_e64 v210, v190, v191, s[82:83]
	v_cndmask_b32_e64 v211, v194, v195, s[84:85]
	v_cndmask_b32_e64 v212, v198, v199, s[86:87]
	v_cndmask_b32_e64 v213, v202, v203, s[88:89]
	s_mov_b32 s90, 0xbfb8aa3b
	v_pk_mul_f32 v[120:121], v[120:121], v[206:207] op_sel_hi:[1,0]
	v_pk_mul_f32 v[122:123], v[122:123], v[206:207] op_sel_hi:[1,0]
	v_pk_mul_f32 v[116:117], v[116:117], v[206:207] op_sel_hi:[1,0]
	v_pk_mul_f32 v[118:119], v[118:119], v[206:207] op_sel_hi:[1,0]
	v_pk_mul_f32 v[124:125], v[124:125], v[206:207] op_sel_hi:[1,0]
	v_pk_mul_f32 v[126:127], v[126:127], v[206:207] op_sel_hi:[1,0]
	v_pk_mul_f32 v[112:113], v[112:113], v[206:207] op_sel_hi:[1,0]
	v_pk_mul_f32 v[114:115], v[114:115], v[206:207] op_sel_hi:[1,0]
	v_pk_mul_f32 v[174:175], v[120:121], s[90:91] op_sel_hi:[1,0]
	v_pk_mul_f32 v[176:177], v[122:123], s[90:91] op_sel_hi:[1,0]
	v_pk_mul_f32 v[178:179], v[116:117], s[90:91] op_sel_hi:[1,0]
	v_pk_mul_f32 v[180:181], v[118:119], s[90:91] op_sel_hi:[1,0]
	v_exp_f32_e32 v174, v174
	v_exp_f32_e32 v175, v175
	v_exp_f32_e32 v176, v176
	v_exp_f32_e32 v177, v177
	v_exp_f32_e32 v178, v178
	v_exp_f32_e32 v179, v179
	v_exp_f32_e32 v180, v180
	v_exp_f32_e32 v181, v181
	v_pk_add_f32 v[174:175], v[174:175], 1.0 op_sel_hi:[1,0]
	v_pk_add_f32 v[176:177], v[176:177], 1.0 op_sel_hi:[1,0]
	v_pk_add_f32 v[178:179], v[178:179], 1.0 op_sel_hi:[1,0]
	v_pk_add_f32 v[180:181], v[180:181], 1.0 op_sel_hi:[1,0]
	v_rcp_f32_e32 v174, v174
	v_rcp_f32_e32 v175, v175
	v_rcp_f32_e32 v176, v176
	v_rcp_f32_e32 v177, v177
	v_rcp_f32_e32 v178, v178
	v_rcp_f32_e32 v179, v179
	v_rcp_f32_e32 v180, v180
	v_rcp_f32_e32 v181, v181
	v_pk_mul_f32 v[120:121], v[120:121], v[174:175]
	v_pk_mul_f32 v[122:123], v[122:123], v[176:177]
	v_pk_mul_f32 v[116:117], v[116:117], v[178:179]
	v_pk_mul_f32 v[118:119], v[118:119], v[180:181]
	v_pk_mul_f32 v[120:121], v[124:125], v[120:121]
	v_pk_mul_f32 v[122:123], v[126:127], v[122:123]
	v_pk_mul_f32 v[116:117], v[112:113], v[116:117]
	v_pk_mul_f32 v[118:119], v[114:115], v[118:119]
	v_cvt_pk_bf16_f32 v120, v120, v121
	v_cvt_pk_bf16_f32 v121, v122, v123
	v_cvt_pk_bf16_f32 v116, v116, v117
	v_cvt_pk_bf16_f32 v117, v118, v119
	global_store_dwordx2 v154, v[120:121], s[34:35]
	global_store_dwordx2 v154, v[116:117], s[34:35] offset:128
	v_pk_mul_f32 v[108:109], v[108:109], v[206:207] op_sel:[0,1] op_sel_hi:[1,1]
	v_pk_mul_f32 v[110:111], v[110:111], v[206:207] op_sel:[0,1] op_sel_hi:[1,1]
	v_pk_mul_f32 v[100:101], v[100:101], v[206:207] op_sel:[0,1] op_sel_hi:[1,1]
	v_pk_mul_f32 v[102:103], v[102:103], v[206:207] op_sel:[0,1] op_sel_hi:[1,1]
	v_pk_mul_f32 v[104:105], v[104:105], v[206:207] op_sel:[0,1] op_sel_hi:[1,1]
	v_pk_mul_f32 v[106:107], v[106:107], v[206:207] op_sel:[0,1] op_sel_hi:[1,1]
	v_pk_mul_f32 v[96:97], v[96:97], v[206:207] op_sel:[0,1] op_sel_hi:[1,1]
	v_pk_mul_f32 v[98:99], v[98:99], v[206:207] op_sel:[0,1] op_sel_hi:[1,1]
	v_pk_mul_f32 v[174:175], v[108:109], s[90:91] op_sel_hi:[1,0]
	v_pk_mul_f32 v[176:177], v[110:111], s[90:91] op_sel_hi:[1,0]
	v_pk_mul_f32 v[178:179], v[100:101], s[90:91] op_sel_hi:[1,0]
	v_pk_mul_f32 v[180:181], v[102:103], s[90:91] op_sel_hi:[1,0]
	v_exp_f32_e32 v174, v174
	v_exp_f32_e32 v175, v175
	v_exp_f32_e32 v176, v176
	v_exp_f32_e32 v177, v177
	v_exp_f32_e32 v178, v178
	v_exp_f32_e32 v179, v179
	v_exp_f32_e32 v180, v180
	v_exp_f32_e32 v181, v181
	v_pk_add_f32 v[174:175], v[174:175], 1.0 op_sel_hi:[1,0]
	v_pk_add_f32 v[176:177], v[176:177], 1.0 op_sel_hi:[1,0]
	v_pk_add_f32 v[178:179], v[178:179], 1.0 op_sel_hi:[1,0]
	v_pk_add_f32 v[180:181], v[180:181], 1.0 op_sel_hi:[1,0]
	v_rcp_f32_e32 v174, v174
	v_rcp_f32_e32 v175, v175
	v_rcp_f32_e32 v176, v176
	v_rcp_f32_e32 v177, v177
	v_rcp_f32_e32 v178, v178
	v_rcp_f32_e32 v179, v179
	v_rcp_f32_e32 v180, v180
	v_rcp_f32_e32 v181, v181
	v_pk_mul_f32 v[108:109], v[108:109], v[174:175]
	v_pk_mul_f32 v[110:111], v[110:111], v[176:177]
	v_pk_mul_f32 v[100:101], v[100:101], v[178:179]
	v_pk_mul_f32 v[102:103], v[102:103], v[180:181]
	v_pk_mul_f32 v[108:109], v[104:105], v[108:109]
	v_pk_mul_f32 v[110:111], v[106:107], v[110:111]
	v_pk_mul_f32 v[100:101], v[96:97], v[100:101]
	v_pk_mul_f32 v[102:103], v[98:99], v[102:103]
	v_cvt_pk_bf16_f32 v108, v108, v109
	v_cvt_pk_bf16_f32 v109, v110, v111
	v_cvt_pk_bf16_f32 v100, v100, v101
	v_cvt_pk_bf16_f32 v101, v102, v103
	global_store_dwordx2 v155, v[108:109], s[34:35]
	global_store_dwordx2 v155, v[100:101], s[34:35] offset:128
	v_pk_mul_f32 v[92:93], v[92:93], v[208:209] op_sel_hi:[1,0]
	v_pk_mul_f32 v[94:95], v[94:95], v[208:209] op_sel_hi:[1,0]
	v_pk_mul_f32 v[84:85], v[84:85], v[208:209] op_sel_hi:[1,0]
	v_pk_mul_f32 v[86:87], v[86:87], v[208:209] op_sel_hi:[1,0]
	v_pk_mul_f32 v[88:89], v[88:89], v[208:209] op_sel_hi:[1,0]
	v_pk_mul_f32 v[90:91], v[90:91], v[208:209] op_sel_hi:[1,0]
	v_pk_mul_f32 v[80:81], v[80:81], v[208:209] op_sel_hi:[1,0]
	v_pk_mul_f32 v[82:83], v[82:83], v[208:209] op_sel_hi:[1,0]
	v_pk_mul_f32 v[174:175], v[92:93], s[90:91] op_sel_hi:[1,0]
	v_pk_mul_f32 v[176:177], v[94:95], s[90:91] op_sel_hi:[1,0]
	v_pk_mul_f32 v[178:179], v[84:85], s[90:91] op_sel_hi:[1,0]
	v_pk_mul_f32 v[180:181], v[86:87], s[90:91] op_sel_hi:[1,0]
	v_exp_f32_e32 v174, v174
	v_exp_f32_e32 v175, v175
	v_exp_f32_e32 v176, v176
	v_exp_f32_e32 v177, v177
	v_exp_f32_e32 v178, v178
	v_exp_f32_e32 v179, v179
	v_exp_f32_e32 v180, v180
	v_exp_f32_e32 v181, v181
	v_pk_add_f32 v[174:175], v[174:175], 1.0 op_sel_hi:[1,0]
	v_pk_add_f32 v[176:177], v[176:177], 1.0 op_sel_hi:[1,0]
	v_pk_add_f32 v[178:179], v[178:179], 1.0 op_sel_hi:[1,0]
	v_pk_add_f32 v[180:181], v[180:181], 1.0 op_sel_hi:[1,0]
	v_rcp_f32_e32 v174, v174
	v_rcp_f32_e32 v175, v175
	v_rcp_f32_e32 v176, v176
	v_rcp_f32_e32 v177, v177
	v_rcp_f32_e32 v178, v178
	v_rcp_f32_e32 v179, v179
	v_rcp_f32_e32 v180, v180
	v_rcp_f32_e32 v181, v181
	v_pk_mul_f32 v[92:93], v[92:93], v[174:175]
	v_pk_mul_f32 v[94:95], v[94:95], v[176:177]
	v_pk_mul_f32 v[84:85], v[84:85], v[178:179]
	v_pk_mul_f32 v[86:87], v[86:87], v[180:181]
	v_pk_mul_f32 v[92:93], v[88:89], v[92:93]
	v_pk_mul_f32 v[94:95], v[90:91], v[94:95]
	v_pk_mul_f32 v[84:85], v[80:81], v[84:85]
	v_pk_mul_f32 v[86:87], v[82:83], v[86:87]
	v_cvt_pk_bf16_f32 v92, v92, v93
	v_cvt_pk_bf16_f32 v93, v94, v95
	v_cvt_pk_bf16_f32 v84, v84, v85
	v_cvt_pk_bf16_f32 v85, v86, v87
	global_store_dwordx2 v156, v[92:93], s[34:35]
	global_store_dwordx2 v156, v[84:85], s[34:35] offset:128
	v_pk_mul_f32 v[76:77], v[76:77], v[208:209] op_sel:[0,1] op_sel_hi:[1,1]
	v_pk_mul_f32 v[78:79], v[78:79], v[208:209] op_sel:[0,1] op_sel_hi:[1,1]
	v_pk_mul_f32 v[68:69], v[68:69], v[208:209] op_sel:[0,1] op_sel_hi:[1,1]
	v_pk_mul_f32 v[70:71], v[70:71], v[208:209] op_sel:[0,1] op_sel_hi:[1,1]
	v_pk_mul_f32 v[72:73], v[72:73], v[208:209] op_sel:[0,1] op_sel_hi:[1,1]
	v_pk_mul_f32 v[74:75], v[74:75], v[208:209] op_sel:[0,1] op_sel_hi:[1,1]
	v_pk_mul_f32 v[64:65], v[64:65], v[208:209] op_sel:[0,1] op_sel_hi:[1,1]
	v_pk_mul_f32 v[66:67], v[66:67], v[208:209] op_sel:[0,1] op_sel_hi:[1,1]
	v_pk_mul_f32 v[174:175], v[76:77], s[90:91] op_sel_hi:[1,0]
	v_pk_mul_f32 v[176:177], v[78:79], s[90:91] op_sel_hi:[1,0]
	v_pk_mul_f32 v[178:179], v[68:69], s[90:91] op_sel_hi:[1,0]
	v_pk_mul_f32 v[180:181], v[70:71], s[90:91] op_sel_hi:[1,0]
	v_exp_f32_e32 v174, v174
	v_exp_f32_e32 v175, v175
	v_exp_f32_e32 v176, v176
	v_exp_f32_e32 v177, v177
	v_exp_f32_e32 v178, v178
	v_exp_f32_e32 v179, v179
	v_exp_f32_e32 v180, v180
	v_exp_f32_e32 v181, v181
	v_pk_add_f32 v[174:175], v[174:175], 1.0 op_sel_hi:[1,0]
	v_pk_add_f32 v[176:177], v[176:177], 1.0 op_sel_hi:[1,0]
	v_pk_add_f32 v[178:179], v[178:179], 1.0 op_sel_hi:[1,0]
	v_pk_add_f32 v[180:181], v[180:181], 1.0 op_sel_hi:[1,0]
	v_rcp_f32_e32 v174, v174
	v_rcp_f32_e32 v175, v175
	v_rcp_f32_e32 v176, v176
	v_rcp_f32_e32 v177, v177
	v_rcp_f32_e32 v178, v178
	v_rcp_f32_e32 v179, v179
	v_rcp_f32_e32 v180, v180
	v_rcp_f32_e32 v181, v181
	v_pk_mul_f32 v[76:77], v[76:77], v[174:175]
	v_pk_mul_f32 v[78:79], v[78:79], v[176:177]
	v_pk_mul_f32 v[68:69], v[68:69], v[178:179]
	v_pk_mul_f32 v[70:71], v[70:71], v[180:181]
	v_pk_mul_f32 v[76:77], v[72:73], v[76:77]
	v_pk_mul_f32 v[78:79], v[74:75], v[78:79]
	v_pk_mul_f32 v[68:69], v[64:65], v[68:69]
	v_pk_mul_f32 v[70:71], v[66:67], v[70:71]
	v_cvt_pk_bf16_f32 v76, v76, v77
	v_cvt_pk_bf16_f32 v77, v78, v79
	v_cvt_pk_bf16_f32 v68, v68, v69
	v_cvt_pk_bf16_f32 v69, v70, v71
	global_store_dwordx2 v157, v[76:77], s[34:35]
	global_store_dwordx2 v157, v[68:69], s[34:35] offset:128
	v_pk_mul_f32 v[60:61], v[60:61], v[210:211] op_sel_hi:[1,0]
	v_pk_mul_f32 v[62:63], v[62:63], v[210:211] op_sel_hi:[1,0]
	v_pk_mul_f32 v[52:53], v[52:53], v[210:211] op_sel_hi:[1,0]
	v_pk_mul_f32 v[54:55], v[54:55], v[210:211] op_sel_hi:[1,0]
	v_pk_mul_f32 v[56:57], v[56:57], v[210:211] op_sel_hi:[1,0]
	v_pk_mul_f32 v[58:59], v[58:59], v[210:211] op_sel_hi:[1,0]
	v_pk_mul_f32 v[48:49], v[48:49], v[210:211] op_sel_hi:[1,0]
	v_pk_mul_f32 v[50:51], v[50:51], v[210:211] op_sel_hi:[1,0]
	v_pk_mul_f32 v[174:175], v[60:61], s[90:91] op_sel_hi:[1,0]
	v_pk_mul_f32 v[176:177], v[62:63], s[90:91] op_sel_hi:[1,0]
	v_pk_mul_f32 v[178:179], v[52:53], s[90:91] op_sel_hi:[1,0]
	v_pk_mul_f32 v[180:181], v[54:55], s[90:91] op_sel_hi:[1,0]
	v_exp_f32_e32 v174, v174
	v_exp_f32_e32 v175, v175
	v_exp_f32_e32 v176, v176
	v_exp_f32_e32 v177, v177
	v_exp_f32_e32 v178, v178
	v_exp_f32_e32 v179, v179
	v_exp_f32_e32 v180, v180
	v_exp_f32_e32 v181, v181
	v_pk_add_f32 v[174:175], v[174:175], 1.0 op_sel_hi:[1,0]
	v_pk_add_f32 v[176:177], v[176:177], 1.0 op_sel_hi:[1,0]
	v_pk_add_f32 v[178:179], v[178:179], 1.0 op_sel_hi:[1,0]
	v_pk_add_f32 v[180:181], v[180:181], 1.0 op_sel_hi:[1,0]
	v_rcp_f32_e32 v174, v174
	v_rcp_f32_e32 v175, v175
	v_rcp_f32_e32 v176, v176
	v_rcp_f32_e32 v177, v177
	v_rcp_f32_e32 v178, v178
	v_rcp_f32_e32 v179, v179
	v_rcp_f32_e32 v180, v180
	v_rcp_f32_e32 v181, v181
	v_pk_mul_f32 v[60:61], v[60:61], v[174:175]
	v_pk_mul_f32 v[62:63], v[62:63], v[176:177]
	v_pk_mul_f32 v[52:53], v[52:53], v[178:179]
	v_pk_mul_f32 v[54:55], v[54:55], v[180:181]
	v_pk_mul_f32 v[60:61], v[56:57], v[60:61]
	v_pk_mul_f32 v[62:63], v[58:59], v[62:63]
	v_pk_mul_f32 v[52:53], v[48:49], v[52:53]
	v_pk_mul_f32 v[54:55], v[50:51], v[54:55]
	v_cvt_pk_bf16_f32 v60, v60, v61
	v_cvt_pk_bf16_f32 v61, v62, v63
	v_cvt_pk_bf16_f32 v52, v52, v53
	v_cvt_pk_bf16_f32 v53, v54, v55
	global_store_dwordx2 v158, v[60:61], s[34:35]
	global_store_dwordx2 v158, v[52:53], s[34:35] offset:128
	v_pk_mul_f32 v[44:45], v[44:45], v[210:211] op_sel:[0,1] op_sel_hi:[1,1]
	v_pk_mul_f32 v[46:47], v[46:47], v[210:211] op_sel:[0,1] op_sel_hi:[1,1]
	v_pk_mul_f32 v[36:37], v[36:37], v[210:211] op_sel:[0,1] op_sel_hi:[1,1]
	v_pk_mul_f32 v[38:39], v[38:39], v[210:211] op_sel:[0,1] op_sel_hi:[1,1]
	v_pk_mul_f32 v[40:41], v[40:41], v[210:211] op_sel:[0,1] op_sel_hi:[1,1]
	v_pk_mul_f32 v[42:43], v[42:43], v[210:211] op_sel:[0,1] op_sel_hi:[1,1]
	v_pk_mul_f32 v[32:33], v[32:33], v[210:211] op_sel:[0,1] op_sel_hi:[1,1]
	v_pk_mul_f32 v[34:35], v[34:35], v[210:211] op_sel:[0,1] op_sel_hi:[1,1]
	v_pk_mul_f32 v[174:175], v[44:45], s[90:91] op_sel_hi:[1,0]
	v_pk_mul_f32 v[176:177], v[46:47], s[90:91] op_sel_hi:[1,0]
	v_pk_mul_f32 v[178:179], v[36:37], s[90:91] op_sel_hi:[1,0]
	v_pk_mul_f32 v[180:181], v[38:39], s[90:91] op_sel_hi:[1,0]
	v_exp_f32_e32 v174, v174
	v_exp_f32_e32 v175, v175
	v_exp_f32_e32 v176, v176
	v_exp_f32_e32 v177, v177
	v_exp_f32_e32 v178, v178
	v_exp_f32_e32 v179, v179
	v_exp_f32_e32 v180, v180
	v_exp_f32_e32 v181, v181
	v_pk_add_f32 v[174:175], v[174:175], 1.0 op_sel_hi:[1,0]
	v_pk_add_f32 v[176:177], v[176:177], 1.0 op_sel_hi:[1,0]
	v_pk_add_f32 v[178:179], v[178:179], 1.0 op_sel_hi:[1,0]
	v_pk_add_f32 v[180:181], v[180:181], 1.0 op_sel_hi:[1,0]
	v_rcp_f32_e32 v174, v174
	v_rcp_f32_e32 v175, v175
	v_rcp_f32_e32 v176, v176
	v_rcp_f32_e32 v177, v177
	v_rcp_f32_e32 v178, v178
	v_rcp_f32_e32 v179, v179
	v_rcp_f32_e32 v180, v180
	v_rcp_f32_e32 v181, v181
	v_pk_mul_f32 v[44:45], v[44:45], v[174:175]
	v_pk_mul_f32 v[46:47], v[46:47], v[176:177]
	v_pk_mul_f32 v[36:37], v[36:37], v[178:179]
	v_pk_mul_f32 v[38:39], v[38:39], v[180:181]
	v_pk_mul_f32 v[44:45], v[40:41], v[44:45]
	v_pk_mul_f32 v[46:47], v[42:43], v[46:47]
	v_pk_mul_f32 v[36:37], v[32:33], v[36:37]
	v_pk_mul_f32 v[38:39], v[34:35], v[38:39]
	v_cvt_pk_bf16_f32 v44, v44, v45
	v_cvt_pk_bf16_f32 v45, v46, v47
	v_cvt_pk_bf16_f32 v36, v36, v37
	v_cvt_pk_bf16_f32 v37, v38, v39
	global_store_dwordx2 v159, v[44:45], s[34:35]
	global_store_dwordx2 v159, v[36:37], s[34:35] offset:128
	v_pk_mul_f32 v[28:29], v[28:29], v[212:213] op_sel_hi:[1,0]
	v_pk_mul_f32 v[30:31], v[30:31], v[212:213] op_sel_hi:[1,0]
	v_pk_mul_f32 v[20:21], v[20:21], v[212:213] op_sel_hi:[1,0]
	v_pk_mul_f32 v[22:23], v[22:23], v[212:213] op_sel_hi:[1,0]
	v_pk_mul_f32 v[24:25], v[24:25], v[212:213] op_sel_hi:[1,0]
	v_pk_mul_f32 v[26:27], v[26:27], v[212:213] op_sel_hi:[1,0]
	v_pk_mul_f32 v[16:17], v[16:17], v[212:213] op_sel_hi:[1,0]
	v_pk_mul_f32 v[18:19], v[18:19], v[212:213] op_sel_hi:[1,0]
	v_pk_mul_f32 v[174:175], v[28:29], s[90:91] op_sel_hi:[1,0]
	v_pk_mul_f32 v[176:177], v[30:31], s[90:91] op_sel_hi:[1,0]
	v_pk_mul_f32 v[178:179], v[20:21], s[90:91] op_sel_hi:[1,0]
	v_pk_mul_f32 v[180:181], v[22:23], s[90:91] op_sel_hi:[1,0]
	v_exp_f32_e32 v174, v174
	v_exp_f32_e32 v175, v175
	v_exp_f32_e32 v176, v176
	v_exp_f32_e32 v177, v177
	v_exp_f32_e32 v178, v178
	v_exp_f32_e32 v179, v179
	v_exp_f32_e32 v180, v180
	v_exp_f32_e32 v181, v181
	v_pk_add_f32 v[174:175], v[174:175], 1.0 op_sel_hi:[1,0]
	v_pk_add_f32 v[176:177], v[176:177], 1.0 op_sel_hi:[1,0]
	v_pk_add_f32 v[178:179], v[178:179], 1.0 op_sel_hi:[1,0]
	v_pk_add_f32 v[180:181], v[180:181], 1.0 op_sel_hi:[1,0]
	v_rcp_f32_e32 v174, v174
	v_rcp_f32_e32 v175, v175
	v_rcp_f32_e32 v176, v176
	v_rcp_f32_e32 v177, v177
	v_rcp_f32_e32 v178, v178
	v_rcp_f32_e32 v179, v179
	v_rcp_f32_e32 v180, v180
	v_rcp_f32_e32 v181, v181
	v_pk_mul_f32 v[28:29], v[28:29], v[174:175]
	v_pk_mul_f32 v[30:31], v[30:31], v[176:177]
	v_pk_mul_f32 v[20:21], v[20:21], v[178:179]
	v_pk_mul_f32 v[22:23], v[22:23], v[180:181]
	v_pk_mul_f32 v[28:29], v[24:25], v[28:29]
	v_pk_mul_f32 v[30:31], v[26:27], v[30:31]
	v_pk_mul_f32 v[20:21], v[16:17], v[20:21]
	v_pk_mul_f32 v[22:23], v[18:19], v[22:23]
	v_cvt_pk_bf16_f32 v28, v28, v29
	v_cvt_pk_bf16_f32 v29, v30, v31
	v_cvt_pk_bf16_f32 v20, v20, v21
	v_cvt_pk_bf16_f32 v21, v22, v23
	global_store_dwordx2 v160, v[28:29], s[34:35]
	global_store_dwordx2 v160, v[20:21], s[34:35] offset:128
	v_pk_mul_f32 v[12:13], v[12:13], v[212:213] op_sel:[0,1] op_sel_hi:[1,1]
	v_pk_mul_f32 v[14:15], v[14:15], v[212:213] op_sel:[0,1] op_sel_hi:[1,1]
	v_pk_mul_f32 v[4:5], v[4:5], v[212:213] op_sel:[0,1] op_sel_hi:[1,1]
	v_pk_mul_f32 v[6:7], v[6:7], v[212:213] op_sel:[0,1] op_sel_hi:[1,1]
	v_pk_mul_f32 v[8:9], v[8:9], v[212:213] op_sel:[0,1] op_sel_hi:[1,1]
	v_pk_mul_f32 v[10:11], v[10:11], v[212:213] op_sel:[0,1] op_sel_hi:[1,1]
	v_pk_mul_f32 v[0:1], v[0:1], v[212:213] op_sel:[0,1] op_sel_hi:[1,1]
	v_pk_mul_f32 v[2:3], v[2:3], v[212:213] op_sel:[0,1] op_sel_hi:[1,1]
	v_pk_mul_f32 v[174:175], v[12:13], s[90:91] op_sel_hi:[1,0]
	v_pk_mul_f32 v[176:177], v[14:15], s[90:91] op_sel_hi:[1,0]
	v_pk_mul_f32 v[178:179], v[4:5], s[90:91] op_sel_hi:[1,0]
	v_pk_mul_f32 v[180:181], v[6:7], s[90:91] op_sel_hi:[1,0]
	v_exp_f32_e32 v174, v174
	v_exp_f32_e32 v175, v175
	v_exp_f32_e32 v176, v176
	v_exp_f32_e32 v177, v177
	v_exp_f32_e32 v178, v178
	v_exp_f32_e32 v179, v179
	v_exp_f32_e32 v180, v180
	v_exp_f32_e32 v181, v181
	v_pk_add_f32 v[174:175], v[174:175], 1.0 op_sel_hi:[1,0]
	v_pk_add_f32 v[176:177], v[176:177], 1.0 op_sel_hi:[1,0]
	v_pk_add_f32 v[178:179], v[178:179], 1.0 op_sel_hi:[1,0]
	v_pk_add_f32 v[180:181], v[180:181], 1.0 op_sel_hi:[1,0]
	v_rcp_f32_e32 v174, v174
	v_rcp_f32_e32 v175, v175
	v_rcp_f32_e32 v176, v176
	v_rcp_f32_e32 v177, v177
	v_rcp_f32_e32 v178, v178
	v_rcp_f32_e32 v179, v179
	v_rcp_f32_e32 v180, v180
	v_rcp_f32_e32 v181, v181
	v_pk_mul_f32 v[12:13], v[12:13], v[174:175]
	v_pk_mul_f32 v[14:15], v[14:15], v[176:177]
	v_pk_mul_f32 v[4:5], v[4:5], v[178:179]
	v_pk_mul_f32 v[6:7], v[6:7], v[180:181]
	v_pk_mul_f32 v[12:13], v[8:9], v[12:13]
	v_pk_mul_f32 v[14:15], v[10:11], v[14:15]
	v_pk_mul_f32 v[4:5], v[0:1], v[4:5]
	v_pk_mul_f32 v[6:7], v[2:3], v[6:7]
	v_cvt_pk_bf16_f32 v12, v12, v13
	v_cvt_pk_bf16_f32 v13, v14, v15
	v_cvt_pk_bf16_f32 v4, v4, v5
	v_cvt_pk_bf16_f32 v5, v6, v7
	global_store_dwordx2 v161, v[12:13], s[34:35]
	global_store_dwordx2 v161, v[4:5], s[34:35] offset:128
	s_setprio 0
	s_andn2_b64 vcc, exec, s[6:7]
	s_mov_b64 s[6:7], -1
	s_cbranch_vccnz .LBB0_543
	s_andn2_b64 vcc, exec, s[14:15]
	s_cbranch_vccnz .LBB0_542
	s_barrier
	s_branch .LBB0_542
